# P5 Q/K epilogue de-serialisation: rope cos/sin of row chunks 2..8 fetched with chunk 1 (one wait) instead of a load+wait per chunk behind the previous stores, on v195
# speedup vs baseline: 1.0001x; 1.0001x over previous
.LBB0_509:
	s_ashr_i32 s54, s8, 3
	s_ashr_i32 s55, s54, 31
	s_and_b32 s25, s8, 7
	s_lshl_b64 s[8:9], s[54:55], 25
	s_add_u32 s52, s74, s8
	s_addc_u32 s53, s75, s9
	v_lshl_add_u32 v168, s10, 8, v157
	v_lshl_or_b32 v184, s25, 8, v179
	s_cmp_lg_u32 s54, 2
	s_mov_b64 s[8:9], -1
	s_cbranch_scc0 .LBB0_512
	s_lshl_b32 s27, s54, 8
	s_cmp_gt_u32 s25, 3
	s_cselect_b64 s[8:9], -1, 0
	s_and_b64 s[10:11], s[8:9], exec
	s_cselect_b32 s10, 0x80, 0
	s_or_b32 s10, s10, s27
	s_ashr_i32 s11, s10, 31
	s_lshl_b64 s[10:11], s[10:11], 2
	s_add_u32 s10, s78, s10
	s_addc_u32 s11, s79, s11
	v_mov_b32_e32 v167, v155
	v_lshl_add_u64 v[130:131], s[10:11], 0, v[166:167]
	s_add_u32 s10, s10, s91
	s_addc_u32 s11, s11, 0
	v_lshlrev_b32_e32 v154, 2, v156
	v_lshl_add_u64 v[134:135], s[10:11], 0, v[154:155]
	v_lshl_add_u64 v[132:133], v[130:131], 0, 64
	v_lshl_add_u64 v[136:137], v[134:135], 0, 16
	v_cndmask_b32_e64 v133, v137, v133, s[4:5]
	v_cndmask_b32_e64 v132, v136, v132, s[4:5]
	v_cndmask_b32_e64 v131, v135, v131, s[4:5]
	v_cndmask_b32_e64 v130, v134, v130, s[4:5]
	global_load_dwordx4 v[134:137], v[130:131], off
	s_nop 0
	global_load_dwordx4 v[130:133], v[132:133], off
	s_and_b64 s[8:9], s[4:5], s[8:9]
	v_cndmask_b32_e64 v138, 0, 1, s[8:9]
	v_cmp_ne_u32_e64 s[10:11], 1, v138
	s_andn2_b64 vcc, exec, s[8:9]
	s_cbranch_vccnz .LBB0_514
	v_lshlrev_b32_e32 v138, 5, v168
	v_and_or_b32 v138, v138, s92, v156
	v_lshlrev_b32_e32 v142, 2, v138
	global_load_dwordx4 v[138:141], v142, s[16:17]
	s_nop 0
	global_load_dwordx4 v[142:145], v142, s[16:17] offset:16
	v_or_b32_e32 v172, 16, v168
	v_lshlrev_b32_e32 v172, 5, v172
	v_and_or_b32 v172, v172, s93, v156
	v_lshlrev_b32_e32 v172, 2, v172
	global_load_dwordx4 v[198:201], v172, s[16:17]
	global_load_dwordx4 v[202:205], v172, s[16:17] offset:16
	v_or_b32_e32 v173, 32, v168
	v_lshlrev_b32_e32 v173, 5, v173
	v_and_or_b32 v173, v173, s94, v156
	v_lshlrev_b32_e32 v173, 2, v173
	global_load_dwordx4 v[206:209], v173, s[16:17]
	global_load_dwordx4 v[210:213], v173, s[16:17] offset:16
	v_or_b32_e32 v172, 48, v168
	v_lshlrev_b32_e32 v172, 5, v172
	v_and_or_b32 v172, v172, s95, v156
	v_lshlrev_b32_e32 v172, 2, v172
	global_load_dwordx4 v[214:217], v172, s[16:17]
	global_load_dwordx4 v[218:221], v172, s[16:17] offset:16
	v_add_u32_e32 v173, 0x80, v168
	v_lshlrev_b32_e32 v173, 5, v173
	v_and_or_b32 v173, v173, s92, v156
	v_lshlrev_b32_e32 v173, 2, v173
	global_load_dwordx4 v[222:225], v173, s[16:17]
	global_load_dwordx4 v[226:229], v173, s[16:17] offset:16
	v_add_u32_e32 v172, 0x90, v168
	v_lshlrev_b32_e32 v172, 5, v172
	v_and_or_b32 v172, v172, s93, v156
	v_lshlrev_b32_e32 v172, 2, v172
	global_load_dwordx4 v[230:233], v172, s[16:17]
	global_load_dwordx4 v[234:237], v172, s[16:17] offset:16
	v_add_u32_e32 v173, 0xa0, v168
	v_lshlrev_b32_e32 v173, 5, v173
	v_and_or_b32 v173, v173, s94, v156
	v_lshlrev_b32_e32 v173, 2, v173
	global_load_dwordx4 v[238:241], v173, s[16:17]
	global_load_dwordx4 v[242:245], v173, s[16:17] offset:16
	v_add_u32_e32 v172, 0xb0, v168
	v_lshlrev_b32_e32 v172, 5, v172
	v_and_or_b32 v172, v172, s95, v156
	v_lshlrev_b32_e32 v172, 2, v172
	global_load_dwordx4 v[246:249], v172, s[16:17]
	global_load_dwordx4 v[250:253], v172, s[16:17] offset:16
	s_waitcnt vmcnt(0)
	v_mov_b32_e32 v172, v139
	v_mov_b32_e32 v139, v140
	v_mov_b32_e32 v173, v141
	v_mov_b32_e32 v140, v143
	v_mov_b32_e32 v143, v144
	v_mov_b32_e32 v141, v145
	s_branch .LBB0_515

.LBB0_519:
	s_or_b64 exec, exec, s[56:57]
	v_pk_mul_f32 v[186:187], v[108:109], v[132:133]
	v_pk_mul_f32 v[188:189], v[106:107], v[130:131]
	s_waitcnt lgkmcnt(0)
	v_pk_mul_f32 v[174:175], v[116:117], v[136:137]
	v_pk_mul_f32 v[176:177], v[114:115], v[134:135]
	v_pk_mul_f32 v[190:191], v[186:187], v[140:141]
	v_pk_mul_f32 v[192:193], v[188:189], v[172:173]
	v_pk_fma_f32 v[190:191], v[174:175], v[142:143], v[190:191] neg_lo:[0,0,1] neg_hi:[0,0,1]
	v_pk_fma_f32 v[192:193], v[176:177], v[138:139], v[192:193] neg_lo:[0,0,1] neg_hi:[0,0,1]
	v_pk_mul_f32 v[142:143], v[186:187], v[142:143]
	v_pk_mul_f32 v[138:139], v[188:189], v[138:139]
	v_pk_fma_f32 v[140:141], v[174:175], v[140:141], v[142:143]
	v_pk_fma_f32 v[138:139], v[176:177], v[172:173], v[138:139]
	v_cndmask_b32_e64 v142, v174, v190, s[8:9]
	v_cndmask_b32_e64 v173, v186, v140, s[8:9]
	v_cndmask_b32_e64 v140, v188, v138, s[8:9]
	v_cndmask_b32_e64 v174, v189, v139, s[8:9]
	v_cndmask_b32_e64 v143, v175, v191, s[8:9]
	v_cndmask_b32_e64 v154, v176, v192, s[8:9]
	v_cndmask_b32_e64 v172, v177, v193, s[8:9]
	v_cndmask_b32_e64 v141, v187, v141, s[8:9]
	v_cvt_pk_bf16_f32 v138, v154, v172
	v_cvt_pk_bf16_f32 v139, v142, v143
	v_cvt_pk_bf16_f32 v140, v140, v174
	s_and_b64 vcc, exec, s[10:11]
	v_or_b32_e32 v174, 16, v168
	v_cvt_pk_bf16_f32 v141, v173, v141
	global_store_dwordx4 v[144:145], v[138:141], off offset:256
	s_cbranch_vccnz .LBB0_521
	s_nop 0
	v_mov_b32_e32 v172, v199
	v_mov_b32_e32 v173, v201
	v_mov_b32_e32 v142, v202
	v_mov_b32_e32 v143, v204
	v_mov_b32_e32 v138, v198
	v_mov_b32_e32 v139, v200
	v_mov_b32_e32 v140, v203
	v_mov_b32_e32 v141, v205
	s_branch .LBB0_522

.LBB0_526:
	s_or_b64 exec, exec, s[56:57]
	v_pk_mul_f32 v[186:187], v[92:93], v[132:133]
	v_pk_mul_f32 v[188:189], v[90:91], v[130:131]
	s_waitcnt lgkmcnt(0)
	v_pk_mul_f32 v[174:175], v[100:101], v[136:137]
	v_pk_mul_f32 v[176:177], v[98:99], v[134:135]
	v_pk_mul_f32 v[190:191], v[186:187], v[140:141]
	v_pk_mul_f32 v[192:193], v[188:189], v[172:173]
	v_pk_fma_f32 v[190:191], v[174:175], v[142:143], v[190:191] neg_lo:[0,0,1] neg_hi:[0,0,1]
	v_pk_fma_f32 v[192:193], v[176:177], v[138:139], v[192:193] neg_lo:[0,0,1] neg_hi:[0,0,1]
	v_pk_mul_f32 v[142:143], v[186:187], v[142:143]
	v_pk_mul_f32 v[138:139], v[188:189], v[138:139]
	v_pk_fma_f32 v[140:141], v[174:175], v[140:141], v[142:143]
	v_pk_fma_f32 v[138:139], v[176:177], v[172:173], v[138:139]
	v_cndmask_b32_e64 v142, v174, v190, s[8:9]
	v_cndmask_b32_e64 v173, v186, v140, s[8:9]
	v_cndmask_b32_e64 v140, v188, v138, s[8:9]
	v_cndmask_b32_e64 v174, v189, v139, s[8:9]
	v_cndmask_b32_e64 v143, v175, v191, s[8:9]
	v_cndmask_b32_e64 v154, v176, v192, s[8:9]
	v_cndmask_b32_e64 v172, v177, v193, s[8:9]
	v_cndmask_b32_e64 v141, v187, v141, s[8:9]
	v_cvt_pk_bf16_f32 v138, v154, v172
	v_cvt_pk_bf16_f32 v139, v142, v143
	v_cvt_pk_bf16_f32 v140, v140, v174
	s_and_b64 vcc, exec, s[10:11]
	v_or_b32_e32 v174, 32, v168
	v_cvt_pk_bf16_f32 v141, v173, v141
	global_store_dwordx4 v[144:145], v[138:141], off offset:256
	s_cbranch_vccnz .LBB0_528
	s_nop 0
	v_mov_b32_e32 v172, v207
	v_mov_b32_e32 v173, v209
	v_mov_b32_e32 v142, v210
	v_mov_b32_e32 v143, v212
	v_mov_b32_e32 v138, v206
	v_mov_b32_e32 v139, v208
	v_mov_b32_e32 v140, v211
	v_mov_b32_e32 v141, v213
	s_branch .LBB0_529

.LBB0_533:
	s_or_b64 exec, exec, s[56:57]
	v_pk_mul_f32 v[186:187], v[76:77], v[132:133]
	v_pk_mul_f32 v[188:189], v[74:75], v[130:131]
	s_waitcnt lgkmcnt(0)
	v_pk_mul_f32 v[174:175], v[84:85], v[136:137]
	v_pk_mul_f32 v[176:177], v[82:83], v[134:135]
	v_pk_mul_f32 v[190:191], v[186:187], v[140:141]
	v_pk_mul_f32 v[192:193], v[188:189], v[172:173]
	v_pk_fma_f32 v[190:191], v[174:175], v[142:143], v[190:191] neg_lo:[0,0,1] neg_hi:[0,0,1]
	v_pk_fma_f32 v[192:193], v[176:177], v[138:139], v[192:193] neg_lo:[0,0,1] neg_hi:[0,0,1]
	v_pk_mul_f32 v[142:143], v[186:187], v[142:143]
	v_pk_mul_f32 v[138:139], v[188:189], v[138:139]
	v_pk_fma_f32 v[140:141], v[174:175], v[140:141], v[142:143]
	v_pk_fma_f32 v[138:139], v[176:177], v[172:173], v[138:139]
	v_cndmask_b32_e64 v142, v174, v190, s[8:9]
	v_cndmask_b32_e64 v173, v186, v140, s[8:9]
	v_cndmask_b32_e64 v140, v188, v138, s[8:9]
	v_cndmask_b32_e64 v174, v189, v139, s[8:9]
	v_cndmask_b32_e64 v143, v175, v191, s[8:9]
	v_cndmask_b32_e64 v154, v176, v192, s[8:9]
	v_cndmask_b32_e64 v172, v177, v193, s[8:9]
	v_cndmask_b32_e64 v141, v187, v141, s[8:9]
	v_cvt_pk_bf16_f32 v138, v154, v172
	v_cvt_pk_bf16_f32 v139, v142, v143
	v_cvt_pk_bf16_f32 v140, v140, v174
	s_and_b64 vcc, exec, s[10:11]
	v_or_b32_e32 v174, 48, v168
	v_cvt_pk_bf16_f32 v141, v173, v141
	global_store_dwordx4 v[144:145], v[138:141], off offset:256
	s_cbranch_vccnz .LBB0_535
	s_nop 0
	v_mov_b32_e32 v172, v215
	v_mov_b32_e32 v173, v217
	v_mov_b32_e32 v142, v218
	v_mov_b32_e32 v143, v220
	v_mov_b32_e32 v138, v214
	v_mov_b32_e32 v139, v216
	v_mov_b32_e32 v140, v219
	v_mov_b32_e32 v141, v221
	s_branch .LBB0_536

.LBB0_540:
	s_or_b64 exec, exec, s[56:57]
	v_pk_mul_f32 v[186:187], v[68:69], v[132:133]
	v_pk_mul_f32 v[188:189], v[66:67], v[130:131]
	s_waitcnt lgkmcnt(0)
	v_pk_mul_f32 v[174:175], v[72:73], v[136:137]
	v_pk_mul_f32 v[176:177], v[70:71], v[134:135]
	v_pk_mul_f32 v[190:191], v[186:187], v[140:141]
	v_pk_mul_f32 v[192:193], v[188:189], v[172:173]
	v_pk_fma_f32 v[190:191], v[174:175], v[142:143], v[190:191] neg_lo:[0,0,1] neg_hi:[0,0,1]
	v_pk_fma_f32 v[192:193], v[176:177], v[138:139], v[192:193] neg_lo:[0,0,1] neg_hi:[0,0,1]
	v_pk_mul_f32 v[142:143], v[186:187], v[142:143]
	v_pk_mul_f32 v[138:139], v[188:189], v[138:139]
	v_pk_fma_f32 v[140:141], v[174:175], v[140:141], v[142:143]
	v_pk_fma_f32 v[138:139], v[176:177], v[172:173], v[138:139]
	v_cndmask_b32_e64 v142, v174, v190, s[8:9]
	v_cndmask_b32_e64 v173, v186, v140, s[8:9]
	v_cndmask_b32_e64 v140, v188, v138, s[8:9]
	v_cndmask_b32_e64 v174, v189, v139, s[8:9]
	v_cndmask_b32_e64 v143, v175, v191, s[8:9]
	v_cndmask_b32_e64 v154, v176, v192, s[8:9]
	v_cndmask_b32_e64 v172, v177, v193, s[8:9]
	v_cndmask_b32_e64 v141, v187, v141, s[8:9]
	v_cvt_pk_bf16_f32 v138, v154, v172
	v_cvt_pk_bf16_f32 v139, v142, v143
	v_cvt_pk_bf16_f32 v140, v140, v174
	s_and_b64 vcc, exec, s[10:11]
	v_add_u32_e32 v174, 0x80, v168
	v_cvt_pk_bf16_f32 v141, v173, v141
	global_store_dwordx4 v[144:145], v[138:141], off offset:256
	s_cbranch_vccnz .LBB0_542
	s_nop 0
	v_mov_b32_e32 v172, v223
	v_mov_b32_e32 v173, v225
	v_mov_b32_e32 v142, v226
	v_mov_b32_e32 v143, v228
	v_mov_b32_e32 v138, v222
	v_mov_b32_e32 v139, v224
	v_mov_b32_e32 v140, v227
	v_mov_b32_e32 v141, v229
	s_branch .LBB0_543

.LBB0_547:
	s_or_b64 exec, exec, s[56:57]
	v_pk_mul_f32 v[186:187], v[44:45], v[132:133]
	v_pk_mul_f32 v[188:189], v[42:43], v[130:131]
	s_waitcnt lgkmcnt(0)
	v_pk_mul_f32 v[174:175], v[52:53], v[136:137]
	v_pk_mul_f32 v[176:177], v[50:51], v[134:135]
	v_pk_mul_f32 v[190:191], v[186:187], v[140:141]
	v_pk_mul_f32 v[192:193], v[188:189], v[172:173]
	v_pk_fma_f32 v[190:191], v[174:175], v[142:143], v[190:191] neg_lo:[0,0,1] neg_hi:[0,0,1]
	v_pk_fma_f32 v[192:193], v[176:177], v[138:139], v[192:193] neg_lo:[0,0,1] neg_hi:[0,0,1]
	v_pk_mul_f32 v[142:143], v[186:187], v[142:143]
	v_pk_mul_f32 v[138:139], v[188:189], v[138:139]
	v_pk_fma_f32 v[140:141], v[174:175], v[140:141], v[142:143]
	v_pk_fma_f32 v[138:139], v[176:177], v[172:173], v[138:139]
	v_cndmask_b32_e64 v142, v174, v190, s[8:9]
	v_cndmask_b32_e64 v173, v186, v140, s[8:9]
	v_cndmask_b32_e64 v140, v188, v138, s[8:9]
	v_cndmask_b32_e64 v174, v189, v139, s[8:9]
	v_cndmask_b32_e64 v143, v175, v191, s[8:9]
	v_cndmask_b32_e64 v154, v176, v192, s[8:9]
	v_cndmask_b32_e64 v172, v177, v193, s[8:9]
	v_cndmask_b32_e64 v141, v187, v141, s[8:9]
	v_cvt_pk_bf16_f32 v138, v154, v172
	v_cvt_pk_bf16_f32 v139, v142, v143
	v_cvt_pk_bf16_f32 v140, v140, v174
	s_and_b64 vcc, exec, s[10:11]
	v_add_u32_e32 v174, 0x90, v168
	v_cvt_pk_bf16_f32 v141, v173, v141
	global_store_dwordx4 v[144:145], v[138:141], off offset:256
	s_cbranch_vccnz .LBB0_549
	s_nop 0
	v_mov_b32_e32 v172, v231
	v_mov_b32_e32 v173, v233
	v_mov_b32_e32 v142, v234
	v_mov_b32_e32 v143, v236
	v_mov_b32_e32 v138, v230
	v_mov_b32_e32 v139, v232
	v_mov_b32_e32 v140, v235
	v_mov_b32_e32 v141, v237
	s_branch .LBB0_550

.LBB0_554:
	s_or_b64 exec, exec, s[56:57]
	v_pk_mul_f32 v[186:187], v[28:29], v[132:133]
	v_pk_mul_f32 v[188:189], v[26:27], v[130:131]
	s_waitcnt lgkmcnt(0)
	v_pk_mul_f32 v[174:175], v[36:37], v[136:137]
	v_pk_mul_f32 v[176:177], v[34:35], v[134:135]
	v_pk_mul_f32 v[190:191], v[186:187], v[140:141]
	v_pk_mul_f32 v[192:193], v[188:189], v[172:173]
	v_pk_fma_f32 v[190:191], v[174:175], v[142:143], v[190:191] neg_lo:[0,0,1] neg_hi:[0,0,1]
	v_pk_fma_f32 v[192:193], v[176:177], v[138:139], v[192:193] neg_lo:[0,0,1] neg_hi:[0,0,1]
	v_pk_mul_f32 v[142:143], v[186:187], v[142:143]
	v_pk_mul_f32 v[138:139], v[188:189], v[138:139]
	v_pk_fma_f32 v[140:141], v[174:175], v[140:141], v[142:143]
	v_pk_fma_f32 v[138:139], v[176:177], v[172:173], v[138:139]
	v_cndmask_b32_e64 v142, v174, v190, s[8:9]
	v_cndmask_b32_e64 v173, v186, v140, s[8:9]
	v_cndmask_b32_e64 v140, v188, v138, s[8:9]
	v_cndmask_b32_e64 v174, v189, v139, s[8:9]
	v_cndmask_b32_e64 v143, v175, v191, s[8:9]
	v_cndmask_b32_e64 v154, v176, v192, s[8:9]
	v_cndmask_b32_e64 v172, v177, v193, s[8:9]
	v_cndmask_b32_e64 v141, v187, v141, s[8:9]
	v_cvt_pk_bf16_f32 v138, v154, v172
	v_cvt_pk_bf16_f32 v139, v142, v143
	v_cvt_pk_bf16_f32 v140, v140, v174
	s_and_b64 vcc, exec, s[10:11]
	v_add_u32_e32 v174, 0xa0, v168
	v_cvt_pk_bf16_f32 v141, v173, v141
	global_store_dwordx4 v[144:145], v[138:141], off offset:256
	s_cbranch_vccnz .LBB0_556
	s_nop 0
	v_mov_b32_e32 v172, v239
	v_mov_b32_e32 v173, v241
	v_mov_b32_e32 v142, v242
	v_mov_b32_e32 v143, v244
	v_mov_b32_e32 v138, v238
	v_mov_b32_e32 v139, v240
	v_mov_b32_e32 v140, v243
	v_mov_b32_e32 v141, v245
	s_branch .LBB0_557

.LBB0_561:
	s_or_b64 exec, exec, s[56:57]
	v_pk_mul_f32 v[186:187], v[12:13], v[132:133]
	v_pk_mul_f32 v[188:189], v[10:11], v[130:131]
	s_waitcnt lgkmcnt(0)
	v_pk_mul_f32 v[174:175], v[20:21], v[136:137]
	v_pk_mul_f32 v[176:177], v[18:19], v[134:135]
	v_pk_mul_f32 v[190:191], v[186:187], v[140:141]
	v_pk_mul_f32 v[192:193], v[188:189], v[172:173]
	v_pk_fma_f32 v[190:191], v[174:175], v[142:143], v[190:191] neg_lo:[0,0,1] neg_hi:[0,0,1]
	v_pk_fma_f32 v[192:193], v[176:177], v[138:139], v[192:193] neg_lo:[0,0,1] neg_hi:[0,0,1]
	v_pk_mul_f32 v[142:143], v[186:187], v[142:143]
	v_pk_mul_f32 v[138:139], v[188:189], v[138:139]
	v_pk_fma_f32 v[140:141], v[174:175], v[140:141], v[142:143]
	v_pk_fma_f32 v[138:139], v[176:177], v[172:173], v[138:139]
	v_cndmask_b32_e64 v154, v176, v192, s[8:9]
	v_cndmask_b32_e64 v173, v186, v140, s[8:9]
	v_cndmask_b32_e64 v141, v187, v141, s[8:9]
	v_cndmask_b32_e64 v140, v188, v138, s[8:9]
	s_and_b64 vcc, exec, s[10:11]
	v_add_u32_e32 v176, 0xb0, v168
	v_cndmask_b32_e64 v142, v174, v190, s[8:9]
	v_cndmask_b32_e64 v143, v175, v191, s[8:9]
	v_cndmask_b32_e64 v172, v177, v193, s[8:9]
	v_cndmask_b32_e64 v174, v189, v139, s[8:9]
	v_cvt_pk_bf16_f32 v138, v154, v172
	v_cvt_pk_bf16_f32 v139, v142, v143
	v_cvt_pk_bf16_f32 v140, v140, v174
	v_cvt_pk_bf16_f32 v141, v173, v141
	global_store_dwordx4 v[144:145], v[138:141], off offset:256
	s_cbranch_vccnz .LBB0_563
	s_nop 0
	v_mov_b32_e32 v172, v247
	v_mov_b32_e32 v173, v249
	v_mov_b32_e32 v142, v250
	v_mov_b32_e32 v143, v252
	v_mov_b32_e32 v138, v246
	v_mov_b32_e32 v139, v248
	v_mov_b32_e32 v174, v251
	v_mov_b32_e32 v175, v253
	s_branch .LBB0_564
